# th13 plus static priority raise for the leading half through its epilogue window
# speedup vs baseline: 1.0023x; 1.0023x over previous
.Lpeel_done_256:
	s_and_b64 vcc, exec, s[12:13]
	s_cbranch_vccz .LBB0_259
	s_barrier
	s_setprio 2

.LBB0_263:
	s_waitcnt lgkmcnt(0)
	v_mul_f32_e32 v152, 0xbfb8aa3b, v174
	v_pk_mul_f32 v[244:245], v[144:145], v[152:153] op_sel_hi:[1,0]
	v_exp_f32_e32 v150, v244
	v_exp_f32_e32 v151, v245
	v_mul_f32_e32 v153, v146, v152
	v_mul_f32_e32 v154, v147, v152
	v_exp_f32_e32 v153, v153
	v_exp_f32_e32 v154, v154
	v_pk_add_f32 v[150:151], v[150:151], 1.0 op_sel_hi:[1,0]
	v_rcp_f32_e32 v150, v150
	v_rcp_f32_e32 v151, v151
	v_pk_mul_f32 v[142:143], v[146:147], v[142:143]
	v_add_f32_e32 v146, 1.0, v153
	v_add_f32_e32 v147, 1.0, v154
	v_rcp_f32_e32 v146, v146
	v_rcp_f32_e32 v147, v147
	v_lshl_or_b32 v149, s47, 7, v193
	v_lshrrev_b32_e32 v246, 4, v172
	v_mul_u32_u24_e32 v246, 0xb0, v246
	v_lshrrev_b32_e32 v247, 5, v149
	v_add_lshl_u32 v246, v246, v247, 10
	v_and_b32_e32 v247, 15, v172
	v_lshl_or_b32 v246, v247, 6, v246
	v_lshrrev_b32_e32 v247, 2, v172
	v_and_b32_e32 v247, 2, v247
	v_bfe_u32 v248, v149, 3, 2
	v_xor_b32_e32 v247, v248, v247
	v_lshl_or_b32 v246, v247, 4, v246
	v_mul_f32_e32 v148, v174, v174
	v_pk_mul_f32 v[140:141], v[144:145], v[140:141]
	v_pk_mul_f32 v[144:145], v[148:149], v[150:151] op_sel_hi:[0,1]
	v_pk_mul_f32 v[140:141], v[140:141], v[144:145]
	v_pk_mul_f32 v[144:145], v[148:149], v[146:147] op_sel_hi:[0,1]
	v_pk_mul_f32 v[146:147], v[136:137], v[152:153] op_sel_hi:[1,0]
	v_exp_f32_e32 v146, v146
	v_exp_f32_e32 v147, v147
	v_pk_mul_f32 v[142:143], v[142:143], v[144:145]
	v_pk_mul_f32 v[134:135], v[138:139], v[134:135]
	v_pk_add_f32 v[144:145], v[146:147], 1.0 op_sel_hi:[1,0]
	v_pk_mul_f32 v[146:147], v[138:139], v[152:153] op_sel_hi:[1,0]
	v_exp_f32_e32 v146, v146
	v_exp_f32_e32 v147, v147
	v_rcp_f32_e32 v144, v144
	v_rcp_f32_e32 v145, v145
	v_pk_add_f32 v[138:139], v[146:147], 1.0 op_sel_hi:[1,0]
	v_rcp_f32_e32 v138, v138
	v_rcp_f32_e32 v139, v139
	v_pk_mul_f32 v[132:133], v[136:137], v[132:133]
	v_pk_mul_f32 v[136:137], v[148:149], v[144:145] op_sel_hi:[0,1]
	v_pk_mul_f32 v[136:137], v[132:133], v[136:137]
	v_pk_mul_f32 v[132:133], v[148:149], v[138:139] op_sel_hi:[0,1]
	s_movk_i32 s6, 0x1600
	v_pk_mul_f32 v[138:139], v[134:135], v[132:133]
	v_cvt_pk_bf16_f32 v134, v136, v137
	v_readlane_b32 s2, v252, 55
	v_cvt_pk_bf16_f32 v132, v140, v141
	v_cvt_pk_bf16_f32 v133, v142, v143
	v_cvt_pk_bf16_f32 v135, v138, v139
	v_readlane_b32 s3, v252, 56
	v_pk_mul_f32 v[126:127], v[130:131], v[126:127]
	v_pk_mul_f32 v[124:125], v[128:129], v[124:125]
	v_pk_mul_f32 v[118:119], v[122:123], v[118:119]
	v_pk_mul_f32 v[116:117], v[120:121], v[116:117]
	v_pk_mul_f32 v[110:111], v[114:115], v[110:111]
	global_store_dwordx4 v246, v[132:135], s[2:3]
	v_pk_mul_f32 v[108:109], v[112:113], v[108:109]
	v_pk_mul_f32 v[102:103], v[106:107], v[102:103]
	v_mul_f32_e32 v133, 0xbfb8aa3b, v175
	v_pk_mul_f32 v[244:245], v[128:129], v[132:133] op_sel:[0,1]
	v_exp_f32_e32 v134, v244
	v_exp_f32_e32 v135, v245
	v_pk_mul_f32 v[136:137], v[130:131], v[132:133] op_sel:[0,1]
	v_exp_f32_e32 v136, v136
	v_exp_f32_e32 v137, v137
	v_pk_add_f32 v[134:135], v[134:135], 1.0 op_sel_hi:[1,0]
	v_rcp_f32_e32 v134, v134
	v_rcp_f32_e32 v135, v135
	v_pk_add_f32 v[130:131], v[136:137], 1.0 op_sel_hi:[1,0]
	v_rcp_f32_e32 v130, v130
	v_rcp_f32_e32 v131, v131
	v_mul_f32_e32 v132, v175, v175
	v_pk_mul_f32 v[128:129], v[132:133], v[134:135] op_sel_hi:[0,1]
	v_pk_mul_f32 v[124:125], v[124:125], v[128:129]
	v_pk_mul_f32 v[128:129], v[132:133], v[130:131] op_sel_hi:[0,1]
	v_pk_mul_f32 v[130:131], v[120:121], v[132:133] op_sel:[0,1]
	v_exp_f32_e32 v130, v130
	v_exp_f32_e32 v131, v131
	v_pk_mul_f32 v[126:127], v[126:127], v[128:129]
	v_pk_mul_f32 v[100:101], v[104:105], v[100:101]
	v_pk_add_f32 v[128:129], v[130:131], 1.0 op_sel_hi:[1,0]
	v_pk_mul_f32 v[130:131], v[122:123], v[132:133] op_sel:[0,1]
	v_exp_f32_e32 v130, v130
	v_exp_f32_e32 v131, v131
	v_rcp_f32_e32 v128, v128
	v_rcp_f32_e32 v129, v129
	v_pk_add_f32 v[122:123], v[130:131], 1.0 op_sel_hi:[1,0]
	v_rcp_f32_e32 v122, v122
	v_rcp_f32_e32 v123, v123
	v_pk_mul_f32 v[120:121], v[132:133], v[128:129] op_sel_hi:[0,1]
	v_pk_mul_f32 v[120:121], v[116:117], v[120:121]
	v_pk_mul_f32 v[94:95], v[98:99], v[94:95]
	v_pk_mul_f32 v[116:117], v[132:133], v[122:123] op_sel_hi:[0,1]
	v_pk_mul_f32 v[122:123], v[118:119], v[116:117]
	v_cvt_pk_bf16_f32 v118, v120, v121
	v_cvt_pk_bf16_f32 v116, v124, v125
	v_cvt_pk_bf16_f32 v117, v126, v127
	v_cvt_pk_bf16_f32 v119, v122, v123
	s_add_u32 s98, s2, 0x2c000
	s_addc_u32 s99, s3, 0
	global_store_dwordx4 v246, v[116:119], s[98:99]
	v_pk_mul_f32 v[92:93], v[96:97], v[92:93]
	v_pk_mul_f32 v[86:87], v[90:91], v[86:87]
	v_mul_f32_e32 v117, 0xbfb8aa3b, v176
	v_pk_mul_f32 v[244:245], v[112:113], v[116:117] op_sel:[0,1]
	v_exp_f32_e32 v118, v244
	v_exp_f32_e32 v119, v245
	v_pk_mul_f32 v[120:121], v[114:115], v[116:117] op_sel:[0,1]
	v_exp_f32_e32 v120, v120
	v_exp_f32_e32 v121, v121
	v_pk_add_f32 v[118:119], v[118:119], 1.0 op_sel_hi:[1,0]
	v_rcp_f32_e32 v118, v118
	v_rcp_f32_e32 v119, v119
	v_pk_add_f32 v[114:115], v[120:121], 1.0 op_sel_hi:[1,0]
	v_rcp_f32_e32 v114, v114
	v_rcp_f32_e32 v115, v115
	v_mul_f32_e32 v116, v176, v176
	v_pk_mul_f32 v[112:113], v[116:117], v[118:119] op_sel_hi:[0,1]
	v_pk_mul_f32 v[108:109], v[108:109], v[112:113]
	v_pk_mul_f32 v[112:113], v[116:117], v[114:115] op_sel_hi:[0,1]
	v_pk_mul_f32 v[114:115], v[104:105], v[116:117] op_sel:[0,1]
	v_exp_f32_e32 v114, v114
	v_exp_f32_e32 v115, v115
	v_pk_mul_f32 v[110:111], v[110:111], v[112:113]
	v_pk_mul_f32 v[84:85], v[88:89], v[84:85]
	v_pk_add_f32 v[112:113], v[114:115], 1.0 op_sel_hi:[1,0]
	v_pk_mul_f32 v[114:115], v[106:107], v[116:117] op_sel:[0,1]
	v_exp_f32_e32 v114, v114
	v_exp_f32_e32 v115, v115
	v_rcp_f32_e32 v112, v112
	v_rcp_f32_e32 v113, v113
	v_pk_add_f32 v[106:107], v[114:115], 1.0 op_sel_hi:[1,0]
	v_rcp_f32_e32 v106, v106
	v_rcp_f32_e32 v107, v107
	v_pk_mul_f32 v[104:105], v[116:117], v[112:113] op_sel_hi:[0,1]
	v_pk_mul_f32 v[104:105], v[100:101], v[104:105]
	v_pk_mul_f32 v[78:79], v[82:83], v[78:79]
	v_pk_mul_f32 v[100:101], v[116:117], v[106:107] op_sel_hi:[0,1]
	v_pk_mul_f32 v[106:107], v[102:103], v[100:101]
	v_cvt_pk_bf16_f32 v102, v104, v105
	v_cvt_pk_bf16_f32 v100, v108, v109
	v_cvt_pk_bf16_f32 v101, v110, v111
	v_cvt_pk_bf16_f32 v103, v106, v107
	s_add_u32 s98, s2, 0x58000
	s_addc_u32 s99, s3, 0
	global_store_dwordx4 v246, v[100:103], s[98:99]
	v_pk_mul_f32 v[76:77], v[80:81], v[76:77]
	v_pk_mul_f32 v[70:71], v[74:75], v[70:71]
	v_mul_f32_e32 v101, 0xbfb8aa3b, v177
	v_pk_mul_f32 v[244:245], v[96:97], v[100:101] op_sel:[0,1]
	v_exp_f32_e32 v102, v244
	v_exp_f32_e32 v103, v245
	v_pk_mul_f32 v[104:105], v[98:99], v[100:101] op_sel:[0,1]
	v_exp_f32_e32 v104, v104
	v_exp_f32_e32 v105, v105
	v_pk_add_f32 v[102:103], v[102:103], 1.0 op_sel_hi:[1,0]
	v_rcp_f32_e32 v102, v102
	v_rcp_f32_e32 v103, v103
	v_pk_add_f32 v[98:99], v[104:105], 1.0 op_sel_hi:[1,0]
	v_rcp_f32_e32 v98, v98
	v_rcp_f32_e32 v99, v99
	v_mul_f32_e32 v100, v177, v177
	v_pk_mul_f32 v[96:97], v[100:101], v[102:103] op_sel_hi:[0,1]
	v_pk_mul_f32 v[92:93], v[92:93], v[96:97]
	v_pk_mul_f32 v[96:97], v[100:101], v[98:99] op_sel_hi:[0,1]
	v_pk_mul_f32 v[98:99], v[88:89], v[100:101] op_sel:[0,1]
	v_exp_f32_e32 v98, v98
	v_exp_f32_e32 v99, v99
	v_pk_mul_f32 v[94:95], v[94:95], v[96:97]
	v_pk_mul_f32 v[68:69], v[72:73], v[68:69]
	v_pk_add_f32 v[96:97], v[98:99], 1.0 op_sel_hi:[1,0]
	v_pk_mul_f32 v[98:99], v[90:91], v[100:101] op_sel:[0,1]
	v_exp_f32_e32 v98, v98
	v_exp_f32_e32 v99, v99
	v_rcp_f32_e32 v96, v96
	v_rcp_f32_e32 v97, v97
	v_pk_add_f32 v[90:91], v[98:99], 1.0 op_sel_hi:[1,0]
	v_rcp_f32_e32 v90, v90
	v_rcp_f32_e32 v91, v91
	v_pk_mul_f32 v[88:89], v[100:101], v[96:97] op_sel_hi:[0,1]
	v_pk_mul_f32 v[88:89], v[84:85], v[88:89]
	v_pk_mul_f32 v[62:63], v[66:67], v[62:63]
	v_pk_mul_f32 v[84:85], v[100:101], v[90:91] op_sel_hi:[0,1]
	v_pk_mul_f32 v[90:91], v[86:87], v[84:85]
	v_cvt_pk_bf16_f32 v86, v88, v89
	v_cvt_pk_bf16_f32 v84, v92, v93
	v_cvt_pk_bf16_f32 v85, v94, v95
	v_cvt_pk_bf16_f32 v87, v90, v91
	s_add_u32 s98, s2, 0x84000
	s_addc_u32 s99, s3, 0
	global_store_dwordx4 v246, v[84:87], s[98:99]
	v_pk_mul_f32 v[60:61], v[64:65], v[60:61]
	v_pk_mul_f32 v[54:55], v[58:59], v[54:55]
	v_mul_f32_e32 v85, 0xbfb8aa3b, v184
	v_pk_mul_f32 v[244:245], v[80:81], v[84:85] op_sel:[0,1]
	v_exp_f32_e32 v86, v244
	v_exp_f32_e32 v87, v245
	v_pk_mul_f32 v[88:89], v[82:83], v[84:85] op_sel:[0,1]
	v_exp_f32_e32 v88, v88
	v_exp_f32_e32 v89, v89
	v_pk_add_f32 v[86:87], v[86:87], 1.0 op_sel_hi:[1,0]
	v_rcp_f32_e32 v86, v86
	v_rcp_f32_e32 v87, v87
	v_pk_add_f32 v[82:83], v[88:89], 1.0 op_sel_hi:[1,0]
	v_rcp_f32_e32 v82, v82
	v_rcp_f32_e32 v83, v83
	v_mul_f32_e32 v84, v184, v184
	v_pk_mul_f32 v[80:81], v[84:85], v[86:87] op_sel_hi:[0,1]
	v_pk_mul_f32 v[76:77], v[76:77], v[80:81]
	v_pk_mul_f32 v[80:81], v[84:85], v[82:83] op_sel_hi:[0,1]
	v_pk_mul_f32 v[82:83], v[72:73], v[84:85] op_sel:[0,1]
	v_exp_f32_e32 v82, v82
	v_exp_f32_e32 v83, v83
	v_pk_mul_f32 v[78:79], v[78:79], v[80:81]
	v_pk_mul_f32 v[52:53], v[56:57], v[52:53]
	v_pk_add_f32 v[80:81], v[82:83], 1.0 op_sel_hi:[1,0]
	v_pk_mul_f32 v[82:83], v[74:75], v[84:85] op_sel:[0,1]
	v_exp_f32_e32 v82, v82
	v_exp_f32_e32 v83, v83
	v_rcp_f32_e32 v80, v80
	v_rcp_f32_e32 v81, v81
	v_pk_add_f32 v[74:75], v[82:83], 1.0 op_sel_hi:[1,0]
	v_rcp_f32_e32 v74, v74
	v_rcp_f32_e32 v75, v75
	v_pk_mul_f32 v[72:73], v[84:85], v[80:81] op_sel_hi:[0,1]
	v_pk_mul_f32 v[72:73], v[68:69], v[72:73]
	v_pk_mul_f32 v[46:47], v[50:51], v[46:47]
	v_pk_mul_f32 v[68:69], v[84:85], v[74:75] op_sel_hi:[0,1]
	v_pk_mul_f32 v[74:75], v[70:71], v[68:69]
	v_cvt_pk_bf16_f32 v70, v72, v73
	v_cvt_pk_bf16_f32 v68, v76, v77
	v_cvt_pk_bf16_f32 v69, v78, v79
	v_cvt_pk_bf16_f32 v71, v74, v75
	s_add_u32 s98, s2, 0x160000
	s_addc_u32 s99, s3, 0
	global_store_dwordx4 v246, v[68:71], s[98:99]
	v_pk_mul_f32 v[44:45], v[48:49], v[44:45]
	v_pk_mul_f32 v[38:39], v[42:43], v[38:39]
	v_mul_f32_e32 v69, 0xbfb8aa3b, v185
	v_pk_mul_f32 v[244:245], v[64:65], v[68:69] op_sel:[0,1]
	v_exp_f32_e32 v70, v244
	v_exp_f32_e32 v71, v245
	v_mul_f32_e32 v73, v66, v69
	v_mul_f32_e32 v74, v67, v69
	v_exp_f32_e32 v73, v73
	v_exp_f32_e32 v74, v74
	v_pk_add_f32 v[70:71], v[70:71], 1.0 op_sel_hi:[1,0]
	v_rcp_f32_e32 v70, v70
	v_rcp_f32_e32 v71, v71
	v_add_f32_e32 v66, 1.0, v73
	v_add_f32_e32 v67, 1.0, v74
	v_rcp_f32_e32 v66, v66
	v_rcp_f32_e32 v67, v67
	v_mul_f32_e32 v68, v185, v185
	v_pk_mul_f32 v[64:65], v[68:69], v[70:71] op_sel_hi:[0,1]
	v_pk_mul_f32 v[60:61], v[60:61], v[64:65]
	v_pk_mul_f32 v[64:65], v[68:69], v[66:67] op_sel_hi:[0,1]
	v_pk_mul_f32 v[66:67], v[56:57], v[68:69] op_sel:[0,1]
	v_exp_f32_e32 v66, v66
	v_exp_f32_e32 v67, v67
	v_pk_mul_f32 v[62:63], v[62:63], v[64:65]
	v_pk_mul_f32 v[36:37], v[40:41], v[36:37]
	v_pk_add_f32 v[64:65], v[66:67], 1.0 op_sel_hi:[1,0]
	v_pk_mul_f32 v[66:67], v[58:59], v[68:69] op_sel:[0,1]
	v_exp_f32_e32 v66, v66
	v_exp_f32_e32 v67, v67
	v_rcp_f32_e32 v64, v64
	v_rcp_f32_e32 v65, v65
	v_pk_add_f32 v[58:59], v[66:67], 1.0 op_sel_hi:[1,0]
	v_rcp_f32_e32 v58, v58
	v_rcp_f32_e32 v59, v59
	v_pk_mul_f32 v[56:57], v[68:69], v[64:65] op_sel_hi:[0,1]
	v_pk_mul_f32 v[56:57], v[52:53], v[56:57]
	v_pk_mul_f32 v[30:31], v[34:35], v[30:31]
	v_pk_mul_f32 v[52:53], v[68:69], v[58:59] op_sel_hi:[0,1]
	v_pk_mul_f32 v[58:59], v[54:55], v[52:53]
	v_cvt_pk_bf16_f32 v52, v60, v61
	v_cvt_pk_bf16_f32 v53, v62, v63
	v_cvt_pk_bf16_f32 v54, v56, v57
	v_cvt_pk_bf16_f32 v55, v58, v59
	s_add_u32 s98, s2, 0x18c000
	s_addc_u32 s99, s3, 0
	global_store_dwordx4 v246, v[52:55], s[98:99]
	v_pk_mul_f32 v[28:29], v[32:33], v[28:29]
	v_pk_mul_f32 v[22:23], v[26:27], v[22:23]
	v_mul_f32_e32 v53, 0xbfb8aa3b, v188
	v_pk_mul_f32 v[244:245], v[48:49], v[52:53] op_sel:[0,1]
	v_exp_f32_e32 v54, v244
	v_exp_f32_e32 v55, v245
	v_pk_mul_f32 v[56:57], v[50:51], v[52:53] op_sel:[0,1]
	v_exp_f32_e32 v56, v56
	v_exp_f32_e32 v57, v57
	v_pk_add_f32 v[54:55], v[54:55], 1.0 op_sel_hi:[1,0]
	v_rcp_f32_e32 v54, v54
	v_rcp_f32_e32 v55, v55
	v_pk_add_f32 v[50:51], v[56:57], 1.0 op_sel_hi:[1,0]
	v_rcp_f32_e32 v50, v50
	v_rcp_f32_e32 v51, v51
	v_mul_f32_e32 v52, v188, v188
	v_pk_mul_f32 v[48:49], v[52:53], v[54:55] op_sel_hi:[0,1]
	v_pk_mul_f32 v[44:45], v[44:45], v[48:49]
	v_pk_mul_f32 v[48:49], v[52:53], v[50:51] op_sel_hi:[0,1]
	v_pk_mul_f32 v[50:51], v[40:41], v[52:53] op_sel:[0,1]
	v_exp_f32_e32 v50, v50
	v_exp_f32_e32 v51, v51
	v_pk_mul_f32 v[46:47], v[46:47], v[48:49]
	v_pk_mul_f32 v[20:21], v[24:25], v[20:21]
	v_pk_add_f32 v[48:49], v[50:51], 1.0 op_sel_hi:[1,0]
	v_pk_mul_f32 v[50:51], v[42:43], v[52:53] op_sel:[0,1]
	v_exp_f32_e32 v50, v50
	v_exp_f32_e32 v51, v51
	v_rcp_f32_e32 v48, v48
	v_rcp_f32_e32 v49, v49
	v_pk_add_f32 v[42:43], v[50:51], 1.0 op_sel_hi:[1,0]
	v_rcp_f32_e32 v42, v42
	v_rcp_f32_e32 v43, v43
	v_pk_mul_f32 v[40:41], v[52:53], v[48:49] op_sel_hi:[0,1]
	v_pk_mul_f32 v[40:41], v[36:37], v[40:41]
	s_andn2_b64 vcc, exec, s[36:37]
	v_pk_mul_f32 v[36:37], v[52:53], v[42:43] op_sel_hi:[0,1]
	v_pk_mul_f32 v[42:43], v[38:39], v[36:37]
	v_cvt_pk_bf16_f32 v36, v44, v45
	v_cvt_pk_bf16_f32 v37, v46, v47
	v_cvt_pk_bf16_f32 v38, v40, v41
	v_cvt_pk_bf16_f32 v39, v42, v43
	s_add_u32 s98, s2, 0x1b8000
	s_addc_u32 s99, s3, 0
	global_store_dwordx4 v246, v[36:39], s[98:99]
	s_nop 1
	v_mul_f32_e32 v37, 0xbfb8aa3b, v189
	v_pk_mul_f32 v[244:245], v[32:33], v[36:37] op_sel:[0,1]
	v_exp_f32_e32 v38, v244
	v_exp_f32_e32 v39, v245
	v_pk_mul_f32 v[40:41], v[34:35], v[36:37] op_sel:[0,1]
	v_exp_f32_e32 v40, v40
	v_exp_f32_e32 v41, v41
	v_pk_add_f32 v[38:39], v[38:39], 1.0 op_sel_hi:[1,0]
	v_rcp_f32_e32 v38, v38
	v_rcp_f32_e32 v39, v39
	v_pk_add_f32 v[34:35], v[40:41], 1.0 op_sel_hi:[1,0]
	v_rcp_f32_e32 v34, v34
	v_rcp_f32_e32 v35, v35
	v_mul_f32_e32 v36, v189, v189
	v_pk_mul_f32 v[32:33], v[36:37], v[38:39] op_sel_hi:[0,1]
	v_pk_mul_f32 v[28:29], v[28:29], v[32:33]
	v_pk_mul_f32 v[32:33], v[36:37], v[34:35] op_sel_hi:[0,1]
	v_pk_mul_f32 v[34:35], v[24:25], v[36:37] op_sel:[0,1]
	v_exp_f32_e32 v34, v34
	v_exp_f32_e32 v35, v35
	v_pk_mul_f32 v[30:31], v[30:31], v[32:33]
	v_pk_add_f32 v[32:33], v[34:35], 1.0 op_sel_hi:[1,0]
	v_pk_mul_f32 v[34:35], v[26:27], v[36:37] op_sel:[0,1]
	v_exp_f32_e32 v34, v34
	v_exp_f32_e32 v35, v35
	v_rcp_f32_e32 v32, v32
	v_rcp_f32_e32 v33, v33
	v_pk_add_f32 v[26:27], v[34:35], 1.0 op_sel_hi:[1,0]
	v_rcp_f32_e32 v26, v26
	v_rcp_f32_e32 v27, v27
	v_pk_mul_f32 v[24:25], v[36:37], v[32:33] op_sel_hi:[0,1]
	v_pk_mul_f32 v[24:25], v[20:21], v[24:25]
	v_pk_mul_f32 v[20:21], v[36:37], v[26:27] op_sel_hi:[0,1]
	v_pk_mul_f32 v[26:27], v[22:23], v[20:21]
	v_cvt_pk_bf16_f32 v20, v28, v29
	v_cvt_pk_bf16_f32 v21, v30, v31
	v_cvt_pk_bf16_f32 v22, v24, v25
	v_cvt_pk_bf16_f32 v23, v26, v27
	s_add_u32 s98, s2, 0x1e4000
	s_addc_u32 s99, s3, 0
	global_store_dwordx4 v246, v[20:23], s[98:99]
	s_mov_b64 s[2:3], -1
	s_cbranch_vccnz .LBB0_252
	s_setprio 0
	s_andn2_b64 vcc, exec, s[0:1]
	s_cbranch_vccnz .LBB0_251
	s_barrier
	s_branch .LBB0_251

.Lpeel_done_489:
	s_and_b64 vcc, exec, s[4:5]
	s_cbranch_vccz .LBB0_492
	s_barrier
	s_setprio 2

.LBB0_496:
	s_ashr_i32 s2, s12, 3
	s_ashr_i32 s3, s2, 31
	s_lshl_b64 s[2:3], s[2:3], 25
	v_readlane_b32 s6, v252, 47
	s_add_u32 s2, s6, s2
	v_readlane_b32 s6, v252, 48
	s_addc_u32 s3, s6, s3
	s_lshl_b32 s6, s12, 9
	s_and_b32 s6, s6, 0xe00
	s_or_b32 s6, s6, s51
	v_lshlrev_b32_e32 v140, 12, v160
	v_or3_b32 v142, v140, s6, v163
	s_waitcnt lgkmcnt(0)
	v_pk_mul_f32 v[138:139], v[138:139], v[4:5] op_sel_hi:[1,0]
	v_pk_mul_f32 v[136:137], v[136:137], v[4:5] op_sel_hi:[1,0]
	v_pk_mul_f32 v[140:141], v[134:135], v[4:5] op_sel_hi:[1,0]
	v_pk_mul_f32 v[134:135], v[132:133], v[4:5] op_sel_hi:[1,0]
	v_cvt_pk_bf16_f32 v132, v136, v137
	v_cvt_pk_bf16_f32 v133, v138, v139
	v_cvt_pk_bf16_f32 v134, v134, v135
	v_cvt_pk_bf16_f32 v135, v140, v141
	global_store_dwordx4 v142, v[132:135], s[2:3]
	v_pk_mul_f32 v[126:127], v[126:127], v[4:5] op_sel_hi:[1,0]
	v_pk_mul_f32 v[124:125], v[124:125], v[4:5] op_sel_hi:[1,0]
	v_pk_mul_f32 v[132:133], v[118:119], v[4:5] op_sel_hi:[1,0]
	v_pk_mul_f32 v[118:119], v[116:117], v[4:5] op_sel_hi:[1,0]
	v_cvt_pk_bf16_f32 v116, v124, v125
	v_cvt_pk_bf16_f32 v117, v126, v127
	v_cvt_pk_bf16_f32 v118, v118, v119
	v_cvt_pk_bf16_f32 v119, v132, v133
	global_store_dwordx4 v142, v[116:119], s[2:3] offset:256
	v_pk_mul_f32 v[122:123], v[122:123], v[4:5] op_sel:[0,1]
	v_pk_mul_f32 v[120:121], v[120:121], v[4:5] op_sel:[0,1]
	v_pk_mul_f32 v[118:119], v[130:131], v[4:5] op_sel:[0,1]
	v_pk_mul_f32 v[116:117], v[128:129], v[4:5] op_sel:[0,1]
	v_or_b32_e32 v124, 0x10000, v142
	v_cvt_pk_bf16_f32 v116, v116, v117
	v_cvt_pk_bf16_f32 v117, v118, v119
	v_cvt_pk_bf16_f32 v118, v120, v121
	v_cvt_pk_bf16_f32 v119, v122, v123
	global_store_dwordx4 v124, v[116:119], s[2:3]
	v_pk_mul_f32 v[110:111], v[110:111], v[4:5] op_sel:[0,1]
	v_pk_mul_f32 v[108:109], v[108:109], v[4:5] op_sel:[0,1]
	v_pk_mul_f32 v[116:117], v[102:103], v[4:5] op_sel:[0,1]
	v_pk_mul_f32 v[4:5], v[100:101], v[4:5] op_sel:[0,1]
	v_cvt_pk_bf16_f32 v100, v108, v109
	v_cvt_pk_bf16_f32 v101, v110, v111
	v_cvt_pk_bf16_f32 v102, v4, v5
	v_cvt_pk_bf16_f32 v103, v116, v117
	global_store_dwordx4 v124, v[100:103], s[2:3] offset:256
	v_pk_mul_f32 v[4:5], v[114:115], v[6:7] op_sel_hi:[1,0]
	v_pk_mul_f32 v[92:93], v[92:93], v[6:7] op_sel_hi:[1,0]
	v_pk_mul_f32 v[100:101], v[112:113], v[6:7] op_sel_hi:[1,0]
	v_or_b32_e32 v108, 0x20000, v142
	v_cvt_pk_bf16_f32 v100, v100, v101
	v_cvt_pk_bf16_f32 v101, v4, v5
	v_pk_mul_f32 v[4:5], v[94:95], v[6:7] op_sel_hi:[1,0]
	v_pk_mul_f32 v[94:95], v[86:87], v[6:7] op_sel_hi:[1,0]
	v_pk_mul_f32 v[86:87], v[84:85], v[6:7] op_sel_hi:[1,0]
	v_cvt_pk_bf16_f32 v84, v92, v93
	v_cvt_pk_bf16_f32 v85, v4, v5
	v_cvt_pk_bf16_f32 v86, v86, v87
	v_cvt_pk_bf16_f32 v87, v94, v95
	global_store_dwordx4 v108, v[84:87], s[2:3] offset:256
	v_pk_mul_f32 v[106:107], v[106:107], v[6:7] op_sel_hi:[1,0]
	v_pk_mul_f32 v[102:103], v[104:105], v[6:7] op_sel_hi:[1,0]
	v_or_b32_e32 v85, 0x30000, v142
	v_mov_b32_e32 v84, v7
	v_pk_mul_f32 v[6:7], v[98:99], v[84:85] op_sel_hi:[1,0]
	v_pk_mul_f32 v[4:5], v[96:97], v[84:85] op_sel_hi:[1,0]
	v_pk_mul_f32 v[86:87], v[90:91], v[84:85] op_sel_hi:[1,0]
	v_pk_mul_f32 v[88:89], v[88:89], v[84:85] op_sel_hi:[1,0]
	v_cvt_pk_bf16_f32 v4, v4, v5
	v_cvt_pk_bf16_f32 v5, v6, v7
	v_cvt_pk_bf16_f32 v6, v88, v89
	v_cvt_pk_bf16_f32 v7, v86, v87
	global_store_dwordx4 v85, v[4:7], s[2:3]
	v_pk_mul_f32 v[78:79], v[78:79], v[84:85] op_sel_hi:[1,0]
	v_pk_mul_f32 v[76:77], v[76:77], v[84:85] op_sel_hi:[1,0]
	v_pk_mul_f32 v[6:7], v[82:83], v[84:85] op_sel_hi:[1,0]
	v_pk_mul_f32 v[4:5], v[80:81], v[84:85] op_sel_hi:[1,0]
	v_pk_mul_f32 v[70:71], v[70:71], v[8:9] op_sel_hi:[1,0]
	v_cvt_pk_bf16_f32 v4, v4, v5
	v_cvt_pk_bf16_f32 v5, v6, v7
	v_cvt_pk_bf16_f32 v6, v76, v77
	v_cvt_pk_bf16_f32 v7, v78, v79
	global_store_dwordx4 v85, v[4:7], s[2:3] offset:256
	v_pk_mul_f32 v[68:69], v[68:69], v[8:9] op_sel_hi:[1,0]
	v_add_u32_e32 v76, 0x80000, v142
	v_pk_mul_f32 v[6:7], v[74:75], v[8:9] op_sel_hi:[1,0]
	v_pk_mul_f32 v[4:5], v[72:73], v[8:9] op_sel_hi:[1,0]
	v_pk_mul_f32 v[54:55], v[54:55], v[8:9] op_sel_hi:[1,0]
	v_cvt_pk_bf16_f32 v4, v4, v5
	v_cvt_pk_bf16_f32 v5, v6, v7
	v_cvt_pk_bf16_f32 v6, v68, v69
	v_cvt_pk_bf16_f32 v7, v70, v71
	global_store_dwordx4 v76, v[4:7], s[2:3]
	v_pk_mul_f32 v[52:53], v[52:53], v[8:9] op_sel_hi:[1,0]
	v_pk_mul_f32 v[20:21], v[20:21], v[10:11] op_sel_hi:[1,0]
	v_pk_mul_f32 v[6:7], v[62:63], v[8:9] op_sel_hi:[1,0]
	v_pk_mul_f32 v[4:5], v[60:61], v[8:9] op_sel_hi:[1,0]
	v_mov_b32_e32 v8, v9
	v_cvt_pk_bf16_f32 v4, v4, v5
	v_cvt_pk_bf16_f32 v5, v6, v7
	v_cvt_pk_bf16_f32 v6, v52, v53
	v_cvt_pk_bf16_f32 v7, v54, v55
	global_store_dwordx4 v76, v[4:7], s[2:3] offset:256
	v_pk_mul_f32 v[52:53], v[58:59], v[8:9] op_sel_hi:[1,0]
	v_pk_mul_f32 v[54:55], v[56:57], v[8:9] op_sel_hi:[1,0]
	v_pk_mul_f32 v[6:7], v[66:67], v[8:9] op_sel_hi:[1,0]
	v_pk_mul_f32 v[4:5], v[64:65], v[8:9] op_sel_hi:[1,0]
	v_add_u32_e32 v60, 0x90000, v142
	v_cvt_pk_bf16_f32 v4, v4, v5
	v_cvt_pk_bf16_f32 v5, v6, v7
	v_cvt_pk_bf16_f32 v6, v54, v55
	v_cvt_pk_bf16_f32 v7, v52, v53
	global_store_dwordx4 v60, v[4:7], s[2:3]
	v_pk_mul_f32 v[38:39], v[38:39], v[8:9] op_sel_hi:[1,0]
	v_cvt_pk_bf16_f32 v102, v102, v103
	v_pk_mul_f32 v[6:7], v[46:47], v[8:9] op_sel_hi:[1,0]
	v_pk_mul_f32 v[4:5], v[44:45], v[8:9] op_sel_hi:[1,0]
	v_pk_mul_f32 v[8:9], v[36:37], v[8:9] op_sel_hi:[1,0]
	v_cvt_pk_bf16_f32 v4, v4, v5
	v_cvt_pk_bf16_f32 v5, v6, v7
	v_cvt_pk_bf16_f32 v6, v8, v9
	v_cvt_pk_bf16_f32 v7, v38, v39
	global_store_dwordx4 v60, v[4:7], s[2:3] offset:256
	v_pk_mul_f32 v[8:9], v[42:43], v[10:11] op_sel_hi:[1,0]
	v_pk_mul_f32 v[36:37], v[40:41], v[10:11] op_sel_hi:[1,0]
	v_pk_mul_f32 v[6:7], v[50:51], v[10:11] op_sel_hi:[1,0]
	v_pk_mul_f32 v[4:5], v[48:49], v[10:11] op_sel_hi:[1,0]
	v_add_u32_e32 v38, 0xa0000, v142
	v_cvt_pk_bf16_f32 v4, v4, v5
	v_cvt_pk_bf16_f32 v5, v6, v7
	v_cvt_pk_bf16_f32 v6, v36, v37
	v_cvt_pk_bf16_f32 v7, v8, v9
	global_store_dwordx4 v38, v[4:7], s[2:3]
	v_pk_mul_f32 v[8:9], v[22:23], v[10:11] op_sel_hi:[1,0]
	v_add_u32_e32 v22, 0xb0000, v142
	v_pk_mul_f32 v[6:7], v[30:31], v[10:11] op_sel_hi:[1,0]
	v_pk_mul_f32 v[4:5], v[28:29], v[10:11] op_sel_hi:[1,0]
	v_cvt_pk_bf16_f32 v103, v106, v107
	v_cvt_pk_bf16_f32 v4, v4, v5
	v_cvt_pk_bf16_f32 v5, v6, v7
	v_cvt_pk_bf16_f32 v6, v20, v21
	v_cvt_pk_bf16_f32 v7, v8, v9
	v_mov_b32_e32 v8, v11
	global_store_dwordx4 v38, v[4:7], s[2:3] offset:256
	v_pk_mul_f32 v[10:11], v[26:27], v[8:9] op_sel_hi:[1,0]
	v_pk_mul_f32 v[20:21], v[24:25], v[8:9] op_sel_hi:[1,0]
	v_pk_mul_f32 v[6:7], v[34:35], v[8:9] op_sel_hi:[1,0]
	v_pk_mul_f32 v[4:5], v[32:33], v[8:9] op_sel_hi:[1,0]
	global_store_dwordx4 v108, v[100:103], s[2:3]
	v_cvt_pk_bf16_f32 v4, v4, v5
	v_cvt_pk_bf16_f32 v5, v6, v7
	v_cvt_pk_bf16_f32 v6, v20, v21
	v_cvt_pk_bf16_f32 v7, v10, v11
	global_store_dwordx4 v22, v[4:7], s[2:3]
	v_pk_mul_f32 v[10:11], v[14:15], v[8:9] op_sel_hi:[1,0]
	s_andn2_b64 vcc, exec, s[36:37]
	v_pk_mul_f32 v[6:7], v[18:19], v[8:9] op_sel_hi:[1,0]
	v_pk_mul_f32 v[4:5], v[16:17], v[8:9] op_sel_hi:[1,0]
	v_pk_mul_f32 v[8:9], v[12:13], v[8:9] op_sel_hi:[1,0]
	v_cvt_pk_bf16_f32 v4, v4, v5
	v_cvt_pk_bf16_f32 v5, v6, v7
	v_cvt_pk_bf16_f32 v6, v8, v9
	v_cvt_pk_bf16_f32 v7, v10, v11
	global_store_dwordx4 v22, v[4:7], s[2:3] offset:256
	s_mov_b64 s[2:3], -1
	s_cbranch_vccnz .LBB0_485
	s_setprio 0
	s_andn2_b64 vcc, exec, s[0:1]
	s_cbranch_vccnz .LBB0_484
	s_barrier
	s_branch .LBB0_484

.Lpeel_done_832:
	s_and_b64 vcc, exec, s[18:19]
	s_cbranch_vccz .LBB0_835
	s_barrier
	s_setprio 2
.LBB0_835:
	v_and_b32_e32 v153, 64, v208
	v_xor_b32_e32 v152, 16, v208
	v_add_u32_e32 v154, 64, v153
	v_cmp_lt_i32_e32 vcc, v152, v154
	v_lshl_add_u32 v151, s6, 8, v146
	v_lshl_or_b32 v2, s17, 9, v149
	v_readlane_b32 s2, v254, 39
	v_cndmask_b32_e32 v152, v208, v152, vcc
	v_lshl_add_u32 v2, v151, 12, v2
	v_and_b32_e32 v228, -16, v151
	v_lshlrev_b32_e32 v228, 12, v228
	v_lshrrev_b32_e32 v229, 6, v149
	v_lshlrev_b32_e32 v229, 10, v229
	v_lshl_or_b32 v229, s17, 13, v229
	v_and_b32_e32 v230, 15, v151
	v_lshl_or_b32 v229, v230, 6, v229
	v_bfe_u32 v230, v149, 4, 2
	v_lshrrev_b32_e32 v231, 2, v151
	v_and_b32_e32 v231, 2, v231
	v_xor_b32_e32 v230, v230, v231
	v_lshl_or_b32 v229, v230, 4, v229
	v_add_u32_e32 v229, 0x800, v229
	v_add_u32_e32 v2, v228, v229
	v_readlane_b32 s3, v254, 40
	v_lshlrev_b32_e32 v153, 2, v152
	v_xor_b32_e32 v152, 32, v208
	v_cmp_lt_i32_e32 vcc, v152, v154
	s_nop 1
	global_load_dwordx4 v[154:157], v2, s[2:3] offset:-2048
	global_load_dwordx4 v[158:161], v2, s[2:3] offset:2048
	v_lshl_add_u64 v[144:145], s[2:3], 0, v[2:3]
	v_cndmask_b32_e32 v152, v208, v152, vcc
	v_lshlrev_b32_e32 v152, 2, v152
	s_mov_b32 s99, 0
	s_mov_b32 s98, 0x10000
	v_lshl_add_u64 v[228:229], v[144:145], 0, s[98:99]
	global_load_dwordx4 v[168:171], v[228:229], off offset:2048
	global_load_dwordx4 v[172:175], v[228:229], off offset:-2048
	s_mov_b32 s98, 0x20000
	v_lshl_add_u64 v[230:231], v[144:145], 0, s[98:99]
	global_load_dwordx4 v[176:179], v[230:231], off offset:2048
	global_load_dwordx4 v[180:183], v[230:231], off offset:-2048
	s_mov_b32 s98, 0x30000
	v_lshl_add_u64 v[232:233], v[144:145], 0, s[98:99]
	global_load_dwordx4 v[184:187], v[232:233], off offset:2048
	global_load_dwordx4 v[188:191], v[232:233], off offset:-2048
	s_mov_b32 s98, 0x80000
	v_lshl_add_u64 v[234:235], v[144:145], 0, s[98:99]
	global_load_dwordx4 v[192:195], v[234:235], off offset:-2048
	global_load_dwordx4 v[196:199], v[234:235], off offset:2048
	s_mov_b32 s98, 0x90000
	v_lshl_add_u64 v[236:237], v[144:145], 0, s[98:99]
	global_load_dwordx4 v[200:203], v[236:237], off offset:2048
	global_load_dwordx4 v[204:207], v[236:237], off offset:-2048
	s_mov_b32 s98, 0xa0000
	v_lshl_add_u64 v[238:239], v[144:145], 0, s[98:99]
	global_load_dwordx4 v[212:215], v[238:239], off offset:2048
	global_load_dwordx4 v[216:219], v[238:239], off offset:-2048
	s_mov_b32 s98, 0xb0000
	v_lshl_add_u64 v[240:241], v[144:145], 0, s[98:99]
	global_load_dwordx4 v[220:223], v[240:241], off offset:2048
	global_load_dwordx4 v[224:227], v[240:241], off offset:-2048
	s_waitcnt vmcnt(14)
	v_lshlrev_b32_e32 v162, 16, v154
	v_and_b32_e32 v163, 0xffff0000, v154
	v_pk_fma_f32 v[162:163], v[128:129], s[14:15], v[162:163]
	v_lshlrev_b32_e32 v154, 16, v155
	v_cvt_pk_bf16_f32 v128, v162, v163
	v_fma_f32 v162, v162, v162, 0
	v_and_b32_e32 v155, 0xffff0000, v155
	v_fmac_f32_e32 v162, v163, v163
	v_pk_fma_f32 v[130:131], v[130:131], s[14:15], v[154:155]
	s_nop 0
	v_fmac_f32_e32 v162, v130, v130
	v_cvt_pk_bf16_f32 v129, v130, v131
	v_fmac_f32_e32 v162, v131, v131
	v_lshlrev_b32_e32 v130, 16, v156
	v_and_b32_e32 v131, 0xffff0000, v156
	v_pk_fma_f32 v[124:125], v[124:125], s[14:15], v[130:131]
	s_nop 0
	v_fmac_f32_e32 v162, v124, v124
	v_cvt_pk_bf16_f32 v130, v124, v125
	v_fmac_f32_e32 v162, v125, v125
	v_lshlrev_b32_e32 v124, 16, v157
	v_and_b32_e32 v125, 0xffff0000, v157
	v_pk_fma_f32 v[124:125], v[126:127], s[14:15], v[124:125]
	s_nop 0
	v_fmac_f32_e32 v162, v124, v124
	v_cvt_pk_bf16_f32 v131, v124, v125
	v_fmac_f32_e32 v162, v125, v125
	v_lshlrev_b32_e32 v124, 16, v158
	v_and_b32_e32 v125, 0xffff0000, v158
	v_pk_fma_f32 v[124:125], v[120:121], s[14:15], v[124:125]
	s_nop 0
	v_fmac_f32_e32 v162, v124, v124
	v_cvt_pk_bf16_f32 v120, v124, v125
	v_fmac_f32_e32 v162, v125, v125
	v_lshlrev_b32_e32 v124, 16, v159
	v_and_b32_e32 v125, 0xffff0000, v159
	v_pk_fma_f32 v[122:123], v[122:123], s[14:15], v[124:125]
	s_nop 0
	v_fmac_f32_e32 v162, v122, v122
	v_cvt_pk_bf16_f32 v121, v122, v123
	v_fmac_f32_e32 v162, v123, v123
	v_lshlrev_b32_e32 v122, 16, v160
	v_and_b32_e32 v123, 0xffff0000, v160
	v_pk_fma_f32 v[116:117], v[116:117], s[14:15], v[122:123]
	s_nop 0
	v_fmac_f32_e32 v162, v116, v116
	v_cvt_pk_bf16_f32 v122, v116, v117
	v_fmac_f32_e32 v162, v117, v117
	v_lshlrev_b32_e32 v116, 16, v161
	v_and_b32_e32 v117, 0xffff0000, v161
	v_pk_fma_f32 v[116:117], v[118:119], s[14:15], v[116:117]
	s_nop 0
	v_fmac_f32_e32 v162, v116, v116
	v_fmac_f32_e32 v162, v117, v117
	v_cvt_pk_bf16_f32 v123, v116, v117
	global_store_dwordx4 v2, v[128:131], s[2:3] offset:-2048
	global_store_dwordx4 v2, v[120:123], s[2:3] offset:2048
	ds_bpermute_b32 v2, v153, v162
	s_mov_b32 s2, 0x10000
	v_add_co_u32_e32 v124, vcc, s2, v144
	s_mov_b32 s2, 0x20000
	s_waitcnt lgkmcnt(0)
	v_add_f32_e32 v2, v162, v2
	ds_bpermute_b32 v116, v152, v2
	v_addc_co_u32_e32 v125, vcc, 0, v145, vcc
	s_waitcnt lgkmcnt(0)
	v_add_f32_e32 v2, v2, v116
	s_waitcnt vmcnt(14)
	v_lshlrev_b32_e32 v126, 16, v172
	v_and_b32_e32 v127, 0xffff0000, v172
	v_pk_fma_f32 v[126:127], v[112:113], s[14:15], v[126:127]
	v_lshlrev_b32_e32 v120, 16, v173
	v_cvt_pk_bf16_f32 v112, v126, v127
	v_fma_f32 v126, v126, v126, 0
	v_and_b32_e32 v121, 0xffff0000, v173
	v_fmac_f32_e32 v126, v127, v127
	v_pk_fma_f32 v[114:115], v[114:115], s[14:15], v[120:121]
	s_nop 0
	v_fmac_f32_e32 v126, v114, v114
	v_cvt_pk_bf16_f32 v113, v114, v115
	v_fmac_f32_e32 v126, v115, v115
	v_lshlrev_b32_e32 v114, 16, v174
	v_and_b32_e32 v115, 0xffff0000, v174
	v_pk_fma_f32 v[108:109], v[108:109], s[14:15], v[114:115]
	s_nop 0
	v_fmac_f32_e32 v126, v108, v108
	v_cvt_pk_bf16_f32 v114, v108, v109
	v_fmac_f32_e32 v126, v109, v109
	v_lshlrev_b32_e32 v108, 16, v175
	v_and_b32_e32 v109, 0xffff0000, v175
	v_pk_fma_f32 v[108:109], v[110:111], s[14:15], v[108:109]
	v_add_co_u32_e32 v110, vcc, s2, v144
	v_fmac_f32_e32 v126, v108, v108
	v_cvt_pk_bf16_f32 v115, v108, v109
	v_fmac_f32_e32 v126, v109, v109
	v_lshlrev_b32_e32 v108, 16, v168
	v_and_b32_e32 v109, 0xffff0000, v168
	v_pk_fma_f32 v[108:109], v[104:105], s[14:15], v[108:109]
	v_addc_co_u32_e32 v111, vcc, 0, v145, vcc
	v_fmac_f32_e32 v126, v108, v108
	v_cvt_pk_bf16_f32 v104, v108, v109
	v_fmac_f32_e32 v126, v109, v109
	v_lshlrev_b32_e32 v108, 16, v169
	v_and_b32_e32 v109, 0xffff0000, v169
	v_pk_fma_f32 v[106:107], v[106:107], s[14:15], v[108:109]
	s_mov_b32 s2, 0x30000
	v_fmac_f32_e32 v126, v106, v106
	v_cvt_pk_bf16_f32 v105, v106, v107
	v_fmac_f32_e32 v126, v107, v107
	v_lshlrev_b32_e32 v106, 16, v170
	v_and_b32_e32 v107, 0xffff0000, v170
	v_pk_fma_f32 v[100:101], v[100:101], s[14:15], v[106:107]
	s_nop 0
	v_fmac_f32_e32 v126, v100, v100
	v_cvt_pk_bf16_f32 v106, v100, v101
	v_fmac_f32_e32 v126, v101, v101
	v_lshlrev_b32_e32 v100, 16, v171
	v_and_b32_e32 v101, 0xffff0000, v171
	v_pk_fma_f32 v[100:101], v[102:103], s[14:15], v[100:101]
	s_nop 0
	v_cvt_pk_bf16_f32 v107, v100, v101
	global_store_dwordx4 v[124:125], v[112:115], off offset:-2048
	global_store_dwordx4 v[124:125], v[104:107], off offset:2048
	s_nop 0
	v_fmac_f32_e32 v126, v100, v100
	v_fmac_f32_e32 v126, v101, v101
	ds_bpermute_b32 v100, v153, v126
	s_waitcnt lgkmcnt(0)
	v_add_f32_e32 v100, v126, v100
	ds_bpermute_b32 v101, v152, v100
	s_waitcnt vmcnt(14)
	v_lshlrev_b32_e32 v112, 16, v180
	v_and_b32_e32 v113, 0xffff0000, v180
	v_pk_fma_f32 v[112:113], v[96:97], s[14:15], v[112:113]
	v_lshlrev_b32_e32 v106, 16, v181
	v_cvt_pk_bf16_f32 v96, v112, v113
	v_fma_f32 v112, v112, v112, 0
	v_and_b32_e32 v107, 0xffff0000, v181
	v_fmac_f32_e32 v112, v113, v113
	v_pk_fma_f32 v[98:99], v[98:99], s[14:15], v[106:107]
	s_nop 0
	v_fmac_f32_e32 v112, v98, v98
	v_cvt_pk_bf16_f32 v97, v98, v99
	v_fmac_f32_e32 v112, v99, v99
	v_lshlrev_b32_e32 v98, 16, v182
	v_and_b32_e32 v99, 0xffff0000, v182
	v_pk_fma_f32 v[92:93], v[92:93], s[14:15], v[98:99]
	s_nop 0
	v_fmac_f32_e32 v112, v92, v92
	v_cvt_pk_bf16_f32 v98, v92, v93
	v_fmac_f32_e32 v112, v93, v93
	v_lshlrev_b32_e32 v92, 16, v183
	v_and_b32_e32 v93, 0xffff0000, v183
	v_pk_fma_f32 v[92:93], v[94:95], s[14:15], v[92:93]
	s_nop 0
	v_fmac_f32_e32 v112, v92, v92
	v_cvt_pk_bf16_f32 v99, v92, v93
	v_fmac_f32_e32 v112, v93, v93
	v_lshlrev_b32_e32 v92, 16, v176
	v_and_b32_e32 v93, 0xffff0000, v176
	v_pk_fma_f32 v[92:93], v[88:89], s[14:15], v[92:93]
	s_nop 0
	v_fmac_f32_e32 v112, v92, v92
	v_cvt_pk_bf16_f32 v88, v92, v93
	v_fmac_f32_e32 v112, v93, v93
	v_lshlrev_b32_e32 v92, 16, v177
	v_and_b32_e32 v93, 0xffff0000, v177
	v_pk_fma_f32 v[90:91], v[90:91], s[14:15], v[92:93]
	v_add_co_u32_e32 v92, vcc, s2, v144
	v_fmac_f32_e32 v112, v90, v90
	v_cvt_pk_bf16_f32 v89, v90, v91
	v_fmac_f32_e32 v112, v91, v91
	v_lshlrev_b32_e32 v90, 16, v178
	v_and_b32_e32 v91, 0xffff0000, v178
	v_pk_fma_f32 v[84:85], v[84:85], s[14:15], v[90:91]
	v_addc_co_u32_e32 v93, vcc, 0, v145, vcc
	v_fmac_f32_e32 v112, v84, v84
	v_cvt_pk_bf16_f32 v90, v84, v85
	v_fmac_f32_e32 v112, v85, v85
	v_lshlrev_b32_e32 v84, 16, v179
	v_and_b32_e32 v85, 0xffff0000, v179
	v_pk_fma_f32 v[84:85], v[86:87], s[14:15], v[84:85]
	s_mov_b32 s2, 0x80000
	v_fmac_f32_e32 v112, v84, v84
	v_fmac_f32_e32 v112, v85, v85
	v_cvt_pk_bf16_f32 v91, v84, v85
	ds_bpermute_b32 v84, v153, v112
	global_store_dwordx4 v[110:111], v[96:99], off offset:-2048
	global_store_dwordx4 v[110:111], v[88:91], off offset:2048
	s_waitcnt lgkmcnt(0)
	v_add_f32_e32 v94, v112, v84
	ds_bpermute_b32 v95, v152, v94
	s_waitcnt vmcnt(14)
	v_lshlrev_b32_e32 v96, 16, v188
	v_and_b32_e32 v97, 0xffff0000, v188
	v_pk_fma_f32 v[96:97], v[80:81], s[14:15], v[96:97]
	v_lshlrev_b32_e32 v88, 16, v189
	v_cvt_pk_bf16_f32 v80, v96, v97
	v_fma_f32 v96, v96, v96, 0
	v_and_b32_e32 v89, 0xffff0000, v189
	v_fmac_f32_e32 v96, v97, v97
	v_pk_fma_f32 v[82:83], v[82:83], s[14:15], v[88:89]
	s_nop 0
	v_fmac_f32_e32 v96, v82, v82
	v_cvt_pk_bf16_f32 v81, v82, v83
	v_fmac_f32_e32 v96, v83, v83
	v_lshlrev_b32_e32 v82, 16, v190
	v_and_b32_e32 v83, 0xffff0000, v190
	v_pk_fma_f32 v[76:77], v[76:77], s[14:15], v[82:83]
	s_nop 0
	v_fmac_f32_e32 v96, v76, v76
	v_cvt_pk_bf16_f32 v82, v76, v77
	v_fmac_f32_e32 v96, v77, v77
	v_lshlrev_b32_e32 v76, 16, v191
	v_and_b32_e32 v77, 0xffff0000, v191
	v_pk_fma_f32 v[76:77], v[78:79], s[14:15], v[76:77]
	v_add_co_u32_e32 v78, vcc, s2, v144
	v_fmac_f32_e32 v96, v76, v76
	v_cvt_pk_bf16_f32 v83, v76, v77
	v_fmac_f32_e32 v96, v77, v77
	v_lshlrev_b32_e32 v76, 16, v184
	v_and_b32_e32 v77, 0xffff0000, v184
	v_pk_fma_f32 v[76:77], v[72:73], s[14:15], v[76:77]
	v_addc_co_u32_e32 v79, vcc, 0, v145, vcc
	v_fmac_f32_e32 v96, v76, v76
	v_cvt_pk_bf16_f32 v72, v76, v77
	v_fmac_f32_e32 v96, v77, v77
	v_lshlrev_b32_e32 v76, 16, v185
	v_and_b32_e32 v77, 0xffff0000, v185
	v_pk_fma_f32 v[74:75], v[74:75], s[14:15], v[76:77]
	s_mov_b32 s2, 0x90000
	v_fmac_f32_e32 v96, v74, v74
	v_cvt_pk_bf16_f32 v73, v74, v75
	v_fmac_f32_e32 v96, v75, v75
	v_lshlrev_b32_e32 v74, 16, v186
	v_and_b32_e32 v75, 0xffff0000, v186
	v_pk_fma_f32 v[68:69], v[68:69], s[14:15], v[74:75]
	s_nop 0
	v_fmac_f32_e32 v96, v68, v68
	v_cvt_pk_bf16_f32 v74, v68, v69
	v_fmac_f32_e32 v96, v69, v69
	v_lshlrev_b32_e32 v68, 16, v187
	v_and_b32_e32 v69, 0xffff0000, v187
	v_pk_fma_f32 v[68:69], v[70:71], s[14:15], v[68:69]
	s_nop 0
	v_cvt_pk_bf16_f32 v75, v68, v69
	global_store_dwordx4 v[92:93], v[80:83], off offset:-2048
	global_store_dwordx4 v[92:93], v[72:75], off offset:2048
	v_fmac_f32_e32 v96, v68, v68
	v_fmac_f32_e32 v96, v69, v69
	ds_bpermute_b32 v68, v153, v96
	s_waitcnt lgkmcnt(0)
	v_add_f32_e32 v68, v96, v68
	ds_bpermute_b32 v69, v152, v68
	s_waitcnt vmcnt(15)
	v_lshlrev_b32_e32 v80, 16, v192
	v_and_b32_e32 v81, 0xffff0000, v192
	v_pk_fma_f32 v[80:81], v[64:65], s[14:15], v[80:81]
	v_lshlrev_b32_e32 v70, 16, v193
	v_cvt_pk_bf16_f32 v64, v80, v81
	v_fma_f32 v80, v80, v80, 0
	v_and_b32_e32 v71, 0xffff0000, v193
	v_fmac_f32_e32 v80, v81, v81
	v_pk_fma_f32 v[66:67], v[66:67], s[14:15], v[70:71]
	s_nop 0
	v_fmac_f32_e32 v80, v66, v66
	v_cvt_pk_bf16_f32 v65, v66, v67
	v_fmac_f32_e32 v80, v67, v67
	v_lshlrev_b32_e32 v66, 16, v194
	v_and_b32_e32 v67, 0xffff0000, v194
	v_pk_fma_f32 v[60:61], v[60:61], s[14:15], v[66:67]
	s_nop 0
	v_fmac_f32_e32 v80, v60, v60
	v_cvt_pk_bf16_f32 v66, v60, v61
	v_fmac_f32_e32 v80, v61, v61
	v_lshlrev_b32_e32 v60, 16, v195
	v_and_b32_e32 v61, 0xffff0000, v195
	v_pk_fma_f32 v[60:61], v[62:63], s[14:15], v[60:61]
	v_add_co_u32_e32 v62, vcc, s2, v144
	v_fmac_f32_e32 v80, v60, v60
	v_cvt_pk_bf16_f32 v67, v60, v61
	v_fmac_f32_e32 v80, v61, v61
	s_waitcnt vmcnt(14)
	v_lshlrev_b32_e32 v60, 16, v196
	v_and_b32_e32 v61, 0xffff0000, v196
	v_pk_fma_f32 v[60:61], v[56:57], s[14:15], v[60:61]
	v_addc_co_u32_e32 v63, vcc, 0, v145, vcc
	v_fmac_f32_e32 v80, v60, v60
	v_cvt_pk_bf16_f32 v56, v60, v61
	v_fmac_f32_e32 v80, v61, v61
	v_lshlrev_b32_e32 v60, 16, v197
	v_and_b32_e32 v61, 0xffff0000, v197
	v_pk_fma_f32 v[58:59], v[58:59], s[14:15], v[60:61]
	s_mov_b32 s2, 0xa0000
	v_fmac_f32_e32 v80, v58, v58
	v_cvt_pk_bf16_f32 v57, v58, v59
	v_fmac_f32_e32 v80, v59, v59
	v_lshlrev_b32_e32 v58, 16, v198
	v_and_b32_e32 v59, 0xffff0000, v198
	v_pk_fma_f32 v[52:53], v[52:53], s[14:15], v[58:59]
	s_nop 0
	v_fmac_f32_e32 v80, v52, v52
	v_cvt_pk_bf16_f32 v58, v52, v53
	v_fmac_f32_e32 v80, v53, v53
	v_lshlrev_b32_e32 v52, 16, v199
	v_and_b32_e32 v53, 0xffff0000, v199
	v_pk_fma_f32 v[52:53], v[54:55], s[14:15], v[52:53]
	s_nop 0
	v_cvt_pk_bf16_f32 v59, v52, v53
	global_store_dwordx4 v[78:79], v[64:67], off offset:-2048
	global_store_dwordx4 v[78:79], v[56:59], off offset:2048
	s_nop 0
	v_fmac_f32_e32 v80, v52, v52
	v_fmac_f32_e32 v80, v53, v53
	ds_bpermute_b32 v52, v153, v80
	s_waitcnt lgkmcnt(0)
	v_add_f32_e32 v52, v80, v52
	ds_bpermute_b32 v53, v152, v52
	s_waitcnt vmcnt(14)
	v_lshlrev_b32_e32 v64, 16, v204
	v_and_b32_e32 v65, 0xffff0000, v204
	v_pk_fma_f32 v[64:65], v[48:49], s[14:15], v[64:65]
	v_lshlrev_b32_e32 v58, 16, v205
	v_cvt_pk_bf16_f32 v48, v64, v65
	v_fma_f32 v64, v64, v64, 0
	v_and_b32_e32 v59, 0xffff0000, v205
	v_fmac_f32_e32 v64, v65, v65
	v_pk_fma_f32 v[50:51], v[50:51], s[14:15], v[58:59]
	s_nop 0
	v_fmac_f32_e32 v64, v50, v50
	v_cvt_pk_bf16_f32 v49, v50, v51
	v_fmac_f32_e32 v64, v51, v51
	v_lshlrev_b32_e32 v50, 16, v206
	v_and_b32_e32 v51, 0xffff0000, v206
	v_pk_fma_f32 v[44:45], v[44:45], s[14:15], v[50:51]
	s_nop 0
	v_fmac_f32_e32 v64, v44, v44
	v_cvt_pk_bf16_f32 v50, v44, v45
	v_fmac_f32_e32 v64, v45, v45
	v_lshlrev_b32_e32 v44, 16, v207
	v_and_b32_e32 v45, 0xffff0000, v207
	v_pk_fma_f32 v[44:45], v[46:47], s[14:15], v[44:45]
	v_add_co_u32_e32 v46, vcc, s2, v144
	v_fmac_f32_e32 v64, v44, v44
	v_cvt_pk_bf16_f32 v51, v44, v45
	v_fmac_f32_e32 v64, v45, v45
	v_lshlrev_b32_e32 v44, 16, v200
	v_and_b32_e32 v45, 0xffff0000, v200
	v_pk_fma_f32 v[44:45], v[40:41], s[14:15], v[44:45]
	v_addc_co_u32_e32 v47, vcc, 0, v145, vcc
	v_fmac_f32_e32 v64, v44, v44
	v_cvt_pk_bf16_f32 v40, v44, v45
	v_fmac_f32_e32 v64, v45, v45
	v_lshlrev_b32_e32 v44, 16, v201
	v_and_b32_e32 v45, 0xffff0000, v201
	v_pk_fma_f32 v[42:43], v[42:43], s[14:15], v[44:45]
	s_mov_b32 s2, 0xb0000
	v_fmac_f32_e32 v64, v42, v42
	v_cvt_pk_bf16_f32 v41, v42, v43
	v_fmac_f32_e32 v64, v43, v43
	v_lshlrev_b32_e32 v42, 16, v202
	v_and_b32_e32 v43, 0xffff0000, v202
	v_pk_fma_f32 v[36:37], v[36:37], s[14:15], v[42:43]
	s_nop 0
	v_fmac_f32_e32 v64, v36, v36
	v_cvt_pk_bf16_f32 v42, v36, v37
	v_fmac_f32_e32 v64, v37, v37
	v_lshlrev_b32_e32 v36, 16, v203
	v_and_b32_e32 v37, 0xffff0000, v203
	v_pk_fma_f32 v[36:37], v[38:39], s[14:15], v[36:37]
	s_nop 0
	v_cvt_pk_bf16_f32 v43, v36, v37
	global_store_dwordx4 v[62:63], v[48:51], off offset:-2048
	global_store_dwordx4 v[62:63], v[40:43], off offset:2048
	s_nop 0
	v_fmac_f32_e32 v64, v36, v36
	v_fmac_f32_e32 v64, v37, v37
	ds_bpermute_b32 v36, v153, v64
	s_waitcnt lgkmcnt(0)
	v_add_f32_e32 v36, v64, v36
	ds_bpermute_b32 v37, v152, v36
	s_waitcnt vmcnt(14)
	v_lshlrev_b32_e32 v48, 16, v216
	v_and_b32_e32 v49, 0xffff0000, v216
	v_pk_fma_f32 v[48:49], v[32:33], s[14:15], v[48:49]
	v_lshlrev_b32_e32 v42, 16, v217
	v_cvt_pk_bf16_f32 v32, v48, v49
	v_fma_f32 v48, v48, v48, 0
	v_and_b32_e32 v43, 0xffff0000, v217
	v_fmac_f32_e32 v48, v49, v49
	v_pk_fma_f32 v[34:35], v[34:35], s[14:15], v[42:43]
	s_nop 0
	v_fmac_f32_e32 v48, v34, v34
	v_cvt_pk_bf16_f32 v33, v34, v35
	v_fmac_f32_e32 v48, v35, v35
	v_lshlrev_b32_e32 v34, 16, v218
	v_and_b32_e32 v35, 0xffff0000, v218
	v_pk_fma_f32 v[28:29], v[28:29], s[14:15], v[34:35]
	s_nop 0
	v_fmac_f32_e32 v48, v28, v28
	v_cvt_pk_bf16_f32 v34, v28, v29
	v_fmac_f32_e32 v48, v29, v29
	v_lshlrev_b32_e32 v28, 16, v219
	v_and_b32_e32 v29, 0xffff0000, v219
	v_pk_fma_f32 v[28:29], v[30:31], s[14:15], v[28:29]
	s_nop 0
	v_fmac_f32_e32 v48, v28, v28
	v_cvt_pk_bf16_f32 v35, v28, v29
	v_fmac_f32_e32 v48, v29, v29
	v_lshlrev_b32_e32 v28, 16, v212
	v_and_b32_e32 v29, 0xffff0000, v212
	v_pk_fma_f32 v[28:29], v[24:25], s[14:15], v[28:29]
	s_nop 0
	v_fmac_f32_e32 v48, v28, v28
	v_cvt_pk_bf16_f32 v24, v28, v29
	v_fmac_f32_e32 v48, v29, v29
	v_lshlrev_b32_e32 v28, 16, v213
	v_and_b32_e32 v29, 0xffff0000, v213
	v_pk_fma_f32 v[26:27], v[26:27], s[14:15], v[28:29]
	v_add_co_u32_e32 v28, vcc, s2, v144
	v_fmac_f32_e32 v48, v26, v26
	v_cvt_pk_bf16_f32 v25, v26, v27
	v_fmac_f32_e32 v48, v27, v27
	v_lshlrev_b32_e32 v26, 16, v214
	v_and_b32_e32 v27, 0xffff0000, v214
	v_pk_fma_f32 v[20:21], v[20:21], s[14:15], v[26:27]
	v_addc_co_u32_e32 v29, vcc, 0, v145, vcc
	v_fmac_f32_e32 v48, v20, v20
	v_cvt_pk_bf16_f32 v26, v20, v21
	v_fmac_f32_e32 v48, v21, v21
	v_lshlrev_b32_e32 v20, 16, v215
	v_and_b32_e32 v21, 0xffff0000, v215
	v_pk_fma_f32 v[20:21], v[22:23], s[14:15], v[20:21]
	s_nop 0
	v_fmac_f32_e32 v48, v20, v20
	v_fmac_f32_e32 v48, v21, v21
	v_cvt_pk_bf16_f32 v27, v20, v21
	ds_bpermute_b32 v20, v153, v48
	global_store_dwordx4 v[46:47], v[32:35], off offset:-2048
	global_store_dwordx4 v[46:47], v[24:27], off offset:2048
	s_waitcnt lgkmcnt(0)
	v_add_f32_e32 v30, v48, v20
	ds_bpermute_b32 v31, v152, v30
	s_waitcnt vmcnt(14)
	v_lshlrev_b32_e32 v32, 16, v224
	v_and_b32_e32 v33, 0xffff0000, v224
	v_pk_fma_f32 v[32:33], v[16:17], s[14:15], v[32:33]
	v_lshlrev_b32_e32 v24, 16, v225
	v_cvt_pk_bf16_f32 v16, v32, v33
	v_fma_f32 v32, v32, v32, 0
	v_and_b32_e32 v25, 0xffff0000, v225
	v_fmac_f32_e32 v32, v33, v33
	v_pk_fma_f32 v[18:19], v[18:19], s[14:15], v[24:25]
	s_nop 0
	v_fmac_f32_e32 v32, v18, v18
	v_cvt_pk_bf16_f32 v17, v18, v19
	v_fmac_f32_e32 v32, v19, v19
	v_lshlrev_b32_e32 v18, 16, v226
	v_and_b32_e32 v19, 0xffff0000, v226
	v_pk_fma_f32 v[12:13], v[12:13], s[14:15], v[18:19]
	s_nop 0
	v_fmac_f32_e32 v32, v12, v12
	v_cvt_pk_bf16_f32 v18, v12, v13
	v_fmac_f32_e32 v32, v13, v13
	v_lshlrev_b32_e32 v12, 16, v227
	v_and_b32_e32 v13, 0xffff0000, v227
	v_pk_fma_f32 v[12:13], v[14:15], s[14:15], v[12:13]
	s_nop 0
	v_fmac_f32_e32 v32, v12, v12
	v_cvt_pk_bf16_f32 v19, v12, v13
	v_fmac_f32_e32 v32, v13, v13
	v_lshlrev_b32_e32 v12, 16, v220
	v_and_b32_e32 v13, 0xffff0000, v220
	v_pk_fma_f32 v[12:13], v[8:9], s[14:15], v[12:13]
	s_nop 0
	v_fmac_f32_e32 v32, v12, v12
	v_cvt_pk_bf16_f32 v8, v12, v13
	v_fmac_f32_e32 v32, v13, v13
	v_lshlrev_b32_e32 v12, 16, v221
	v_and_b32_e32 v13, 0xffff0000, v221
	v_pk_fma_f32 v[10:11], v[10:11], s[14:15], v[12:13]
	s_nop 0
	v_fmac_f32_e32 v32, v10, v10
	v_cvt_pk_bf16_f32 v9, v10, v11
	v_fmac_f32_e32 v32, v11, v11
	v_lshlrev_b32_e32 v10, 16, v222
	v_and_b32_e32 v11, 0xffff0000, v222
	v_pk_fma_f32 v[4:5], v[4:5], s[14:15], v[10:11]
	s_nop 0
	v_fmac_f32_e32 v32, v4, v4
	v_cvt_pk_bf16_f32 v10, v4, v5
	v_fmac_f32_e32 v32, v5, v5
	v_lshlrev_b32_e32 v4, 16, v223
	v_and_b32_e32 v5, 0xffff0000, v223
	v_pk_fma_f32 v[4:5], v[6:7], s[14:15], v[4:5]
	s_nop 0
	v_fmac_f32_e32 v32, v4, v4
	v_fmac_f32_e32 v32, v5, v5
	v_cvt_pk_bf16_f32 v11, v4, v5
	ds_bpermute_b32 v4, v153, v32
	global_store_dwordx4 v[28:29], v[16:19], off offset:-2048
	global_store_dwordx4 v[28:29], v[8:11], off offset:2048
	s_waitcnt lgkmcnt(0)
	v_add_f32_e32 v4, v32, v4
	ds_bpermute_b32 v5, v152, v4
	s_and_saveexec_b64 s[2:3], s[38:39]
	s_setprio 0
	v_add_f32_e32 v2, v30, v31
	v_add_f32_e32 v6, v52, v53
	v_add_f32_e32 v7, v94, v95
	v_cndmask_b32_e64 v2, v2, v6, s[42:43]
	v_cndmask_b32_e64 v2, v2, v7, s[40:41]
	s_or_b64 exec, exec, s[2:3]
	v_add_f32_e32 v8, v36, v37
	s_waitcnt lgkmcnt(0)
	v_add_f32_e32 v4, v4, v5
	v_add_f32_e32 v7, v68, v69
	v_cndmask_b32_e64 v4, v4, v8, s[42:43]
	v_add_f32_e32 v6, v100, v101
	v_cndmask_b32_e64 v4, v4, v7, s[40:41]
	v_cndmask_b32_e64 v6, v4, v6, s[36:37]
	v_add_u32_e32 v4, v148, v151
	v_ashrrev_i32_e32 v5, 31, v4
	v_readlane_b32 s2, v252, 45
	v_lshlrev_b64 v[4:5], 7, v[4:5]
	v_readlane_b32 s3, v252, 46
	s_and_b64 vcc, exec, s[44:45]
	s_nop 0
	v_lshl_add_u64 v[4:5], s[2:3], 0, v[4:5]
	s_lshl_b32 s2, s17, 2
	s_ashr_i32 s3, s2, 31
	v_lshl_add_u64 v[4:5], s[2:3], 2, v[4:5]
	v_readlane_b32 s2, v255, 9
	v_readlane_b32 s3, v255, 10
	s_nop 1
	v_lshl_add_u64 v[4:5], v[4:5], 0, s[2:3]
	s_mov_b64 s[2:3], -1
	global_store_dword v[4:5], v2, off
	global_store_dword v[4:5], v6, off offset:2048
	s_cbranch_vccnz .LBB0_820
	s_andn2_b64 vcc, exec, s[12:13]
	s_cbranch_vccnz .LBB0_819
	s_barrier
	s_branch .LBB0_819
